# static s_setprio 1 at kernel entry for waves 0-3 instead of 4-7
# speedup vs baseline: 1.0006x; 1.0006x over previous
_Z14fwd_megakernel6Params:
	s_load_dwordx2 s[70:71], s[0:1], 0x128
	s_load_dword s33, s[0:1], 0x130
	s_mov_b64 s[66:67], s[0:1]
	s_add_u32 s0, s66, 0x128
	v_and_b32_e32 v178, 0x3ff, v0
	s_mov_b32 s68, s2
	s_addc_u32 s1, s67, 0
	v_readfirstlane_b32 s32, v0
	s_nop 3
	s_bfe_u32 s32, s32, 0x40006
	s_cmp_ge_u32 s32, 4
	s_cbranch_scc1 .Lprio_done
	s_setprio 1
